# up-GEMM k-loop: m0 writes hoisted ahead of the interleaved ds_reads so no s_nop pads remain in the load segments (on top of 4/4/4/4 staging, SGPR-base DMA, DMA/ds_read interleave)
# speedup vs baseline: 1.0041x; 1.0004x over previous
; #define PG8_STAGE(bufoff, gbase, voff) do { _Pragma("unroll") for (int _i = 0; _i < 2; ++_i) \
;         __builtin_amdgcn_global_load_lds((const unsigned*)((const char*)(gbase) + (voff)[_i]), (LAS unsigned*)(lds + (bufoff) + ldsw + _i * 8192), 16, 0, 0); } while (0)
; #define PG8_LDA(dst, b, h) do { _Pragma("unroll") for (int m = 0; m < 4; ++m) _Pragma("unroll") for (int k = 0; k < 2; ++k) dst[m][k] = *(const LAS bf16x8*)(lds + PG8_SA(b, h) + aoff + m * 2048 + k * 1024); } while (0)
; #define PG8_LDB(dst, b, h) do { _Pragma("unroll") for (int n = 0; n < 2; ++n) _Pragma("unroll") for (int k = 0; k < 2; ++k) dst[n][k] = *(const LAS bf16x8*)(lds + PG8_SB(b, h) + boff + n * 2048 + k * 1024); } while (0)
; #define PG8_MMA(ai, bj, At, Bt) do { __builtin_amdgcn_s_setprio(1); _Pragma("unroll") for (int m = 0; m < 4; ++m) _Pragma("unroll") for (int n = 0; n < 2; ++n) _Pragma("unroll") for (int k = 0; k < 2; ++k) \
;         acc[ai][bj][m][n] = __builtin_amdgcn_mfma_f32_16x16x32_bf16(Bt[n][k], At[m][k], acc[ai][bj][m][n], 0, 0, 0); __builtin_amdgcn_s_setprio(0); } while (0)
; #define PG8_WAIT_V(n) asm volatile("s_waitcnt vmcnt(" #n ")" ::: "memory")
; #define PG8_WAIT_L(n) asm volatile("s_waitcnt lgkmcnt(" #n ")" ::: "memory")
; #define PG8_BAR __builtin_amdgcn_s_barrier()
; template <class Epi, class Sched, bool ALIGN_EPI = false, bool SP2 = false>
; __device__ __forceinline__ void gemm_phase(LAS unsigned char* lds, const Gemm g, const Sched& S, const Epi& E, int wid) {
;     ...
;         for (int t = 0; t < nt; t += 2) {
;             const bool last = (t == nt - 2);
;             const char* a1 = cA + (size_t)(t + 1) * kstep;
;             const char* a2 = last ? nA : cA + (size_t)(t + 2) * kstep; const char* b2 = last ? nB : cB + (size_t)(t + 2) * kstep;
;             const char* a3 = a2 + kstep; const char* b3 = b2 + kstep;
;             if constexpr (SP2) {
;             PG8_LDB(B0, 0, 0); PG8_LDB(B1, 0, 1); PG8_SCHED; PG8_LDA(At, 0, 0); PG8_STAGE(PG8_SA(1, 1), a1 + hstepA, voffA);
;             PG8_WAIT_V(8); PG8_WAIT_L(0); PG8_BAR; PG8_MMA(0, 0, At, B0); PG8_MMA(0, 1, At, B1); PG8_BAR; PG8_SCHED;
;             PG8_LDA(At, 0, 1); PG8_STAGE(PG8_SB(0, 0), b2, voffB); PG8_STAGE(PG8_SB(0, 1), b2 + hstepB, voffB); PG8_STAGE(PG8_SA(0, 0), a2, voffA);
;             PG8_WAIT_V(8); PG8_WAIT_L(0); PG8_BAR; PG8_MMA(1, 0, At, B0); PG8_MMA(1, 1, At, B1); PG8_BAR; PG8_SCHED;
.LBB0_968:
	s_add_u32 s56, s54, 0x100
	s_addc_u32 s57, s55, 0
	s_add_i32 s62, 0, 0x10000
	s_cmp_eq_u32 s93, 28
	s_cselect_b32 s49, s41, s57
	s_cselect_b32 s48, s42, s56
	s_cselect_b32 vcc_hi, s43, s61
	s_cselect_b32 vcc_lo, s59, s60
	s_add_i32 s63, 0, 0x14000
	v_add_u32_e32 v116, s62, v228
	v_add_u32_e32 v132, s63, v228
	s_mov_b32 m0, s94
	s_add_u32 s100, s54, 0x80
	s_addc_u32 s101, s55, 0
	global_load_lds_dwordx4 v176, s[100:101]
	s_mov_b32 m0, s95
	ds_read_b128 v[104:107], v116
	ds_read_b128 v[108:111], v116 offset:1024
	ds_read_b128 v[112:115], v116 offset:2048
	ds_read_b128 v[116:119], v116 offset:3072
	global_load_lds_dwordx4 v174, s[100:101]
	ds_read_b128 v[120:123], v132
	ds_read_b128 v[124:127], v132 offset:1024
	ds_read_b128 v[128:131], v132 offset:2048
	ds_read_b128 v[132:135], v132 offset:3072
	s_add_i32 m0, s79, 0xc000
	s_add_u32 s100, s100, 0x80000
	s_addc_u32 s101, s101, 0
	global_load_lds_dwordx4 v176, s[100:101]
	s_add_i32 m0, s79, 0xe000
	ds_read_b128 v[144:147], v231
	ds_read_b128 v[164:167], v231 offset:1024
	ds_read_b128 v[168:171], v231 offset:2048
	ds_read_b128 v[186:189], v231 offset:3072
	global_load_lds_dwordx4 v174, s[100:101]
	ds_read_b128 v[200:203], v231 offset:4096
	ds_read_b128 v[204:207], v231 offset:5120
	ds_read_b128 v[208:211], v231 offset:6144
	ds_read_b128 v[212:215], v231 offset:7168
	s_waitcnt vmcnt(8)
	s_waitcnt lgkmcnt(0)
	s_barrier
	s_setprio 1
	s_waitcnt lgkmcnt(0)
	v_mfma_f32_16x16x32_bf16 v[160:163], v[104:107], v[144:147], v[160:163]
	v_mfma_f32_16x16x32_bf16 v[60:63], v[112:115], v[144:147], v[60:63]
	v_mfma_f32_16x16x32_bf16 v[152:155], v[104:107], v[168:171], v[152:155]
	v_mfma_f32_16x16x32_bf16 v[36:39], v[112:115], v[168:171], v[36:39]
	v_mfma_f32_16x16x32_bf16 v[140:143], v[104:107], v[200:203], v[140:143]
	v_mfma_f32_16x16x32_bf16 v[56:59], v[112:115], v[200:203], v[56:59]
	v_mfma_f32_16x16x32_bf16 v[100:103], v[104:107], v[208:211], v[100:103]
	v_mfma_f32_16x16x32_bf16 v[48:51], v[112:115], v[208:211], v[48:51]
	v_mfma_f32_16x16x32_bf16 v[160:163], v[108:111], v[164:167], v[160:163]
	v_mfma_f32_16x16x32_bf16 v[60:63], v[116:119], v[164:167], v[60:63]
	v_mfma_f32_16x16x32_bf16 v[152:155], v[108:111], v[186:189], v[152:155]
	v_mfma_f32_16x16x32_bf16 v[36:39], v[116:119], v[186:189], v[36:39]
	v_mfma_f32_16x16x32_bf16 v[140:143], v[108:111], v[204:207], v[140:143]
	v_mfma_f32_16x16x32_bf16 v[56:59], v[116:119], v[204:207], v[56:59]
	v_mfma_f32_16x16x32_bf16 v[100:103], v[108:111], v[212:215], v[100:103]
	v_mfma_f32_16x16x32_bf16 v[48:51], v[116:119], v[212:215], v[48:51]
	s_setprio 0
	s_setprio 1
	v_mfma_f32_16x16x32_bf16 v[156:159], v[120:123], v[144:147], v[156:159]
	v_mfma_f32_16x16x32_bf16 v[52:55], v[128:131], v[144:147], v[52:55]
	v_mfma_f32_16x16x32_bf16 v[32:35], v[128:131], v[168:171], v[32:35]
	v_mfma_f32_16x16x32_bf16 v[136:139], v[120:123], v[200:203], v[136:139]
	v_mfma_f32_16x16x32_bf16 v[44:47], v[128:131], v[200:203], v[44:47]
	v_mfma_f32_16x16x32_bf16 v[96:99], v[120:123], v[208:211], v[96:99]
	v_mfma_f32_16x16x32_bf16 v[40:43], v[128:131], v[208:211], v[40:43]
	v_mfma_f32_16x16x32_bf16 v[156:159], v[124:127], v[164:167], v[156:159]
	v_mfma_f32_16x16x32_bf16 v[52:55], v[132:135], v[164:167], v[52:55]
	v_mfma_f32_16x16x32_bf16 v[144:147], v[120:123], v[168:171], v[148:151]
	v_mfma_f32_16x16x32_bf16 v[32:35], v[132:135], v[186:189], v[32:35]
	v_mfma_f32_16x16x32_bf16 v[136:139], v[124:127], v[204:207], v[136:139]
	v_mfma_f32_16x16x32_bf16 v[44:47], v[132:135], v[204:207], v[44:47]
	v_mfma_f32_16x16x32_bf16 v[96:99], v[124:127], v[212:215], v[96:99]
	v_mfma_f32_16x16x32_bf16 v[40:43], v[132:135], v[212:215], v[40:43]
	v_mfma_f32_16x16x32_bf16 v[144:147], v[124:127], v[186:189], v[144:147]
	s_setprio 0
	s_barrier
	s_add_i32 s54, s62, s89
	s_mov_b32 m0, s54
	s_mov_b64 s[100:101], vcc
	global_load_lds_dwordx4 v192, s[100:101]
	s_add_i32 m0, s54, 0x2000
	ds_read_b128 v[148:151], v231 offset:16384
	ds_read_b128 v[164:167], v231 offset:17408
	s_add_u32 s54, vcc_lo, 0x80000
	s_addc_u32 s55, vcc_hi, 0
	s_add_i32 s62, s63, s89
	global_load_lds_dwordx4 v172, s[100:101]
	s_mov_b32 m0, s62
	ds_read_b128 v[168:171], v231 offset:18432
	ds_read_b128 v[186:189], v231 offset:19456
	global_load_lds_dwordx4 v192, s[54:55]
	s_add_i32 m0, s62, 0x2000
	ds_read_b128 v[200:203], v231 offset:20480
	ds_read_b128 v[204:207], v231 offset:21504
	global_load_lds_dwordx4 v172, s[54:55]
	ds_read_b128 v[208:211], v231 offset:22528
	ds_read_b128 v[212:215], v231 offset:23552
	s_waitcnt vmcnt(6)
	s_waitcnt lgkmcnt(0)
	s_barrier
; #define PG8_STAGE(bufoff, gbase, voff) do { _Pragma("unroll") for (int _i = 0; _i < 2; ++_i) \
;         __builtin_amdgcn_global_load_lds((const unsigned*)((const char*)(gbase) + (voff)[_i]), (LAS unsigned*)(lds + (bufoff) + ldsw + _i * 8192), 16, 0, 0); } while (0)
; #define PG8_LDA(dst, b, h) do { _Pragma("unroll") for (int m = 0; m < 4; ++m) _Pragma("unroll") for (int k = 0; k < 2; ++k) dst[m][k] = *(const LAS bf16x8*)(lds + PG8_SA(b, h) + aoff + m * 2048 + k * 1024); } while (0)
; #define PG8_LDB(dst, b, h) do { _Pragma("unroll") for (int n = 0; n < 2; ++n) _Pragma("unroll") for (int k = 0; k < 2; ++k) dst[n][k] = *(const LAS bf16x8*)(lds + PG8_SB(b, h) + boff + n * 2048 + k * 1024); } while (0)
; #define PG8_MMA(ai, bj, At, Bt) do { __builtin_amdgcn_s_setprio(1); _Pragma("unroll") for (int m = 0; m < 4; ++m) _Pragma("unroll") for (int n = 0; n < 2; ++n) _Pragma("unroll") for (int k = 0; k < 2; ++k) \
;         acc[ai][bj][m][n] = __builtin_amdgcn_mfma_f32_16x16x32_bf16(Bt[n][k], At[m][k], acc[ai][bj][m][n], 0, 0, 0); __builtin_amdgcn_s_setprio(0); } while (0)
; #define PG8_WAIT_V(n) asm volatile("s_waitcnt vmcnt(" #n ")" ::: "memory")
; #define PG8_WAIT_L(n) asm volatile("s_waitcnt lgkmcnt(" #n ")" ::: "memory")
; #define PG8_BAR __builtin_amdgcn_s_barrier()
; #define PG8_SCHED __builtin_amdgcn_sched_barrier(0)
; template <class Epi, class Sched, bool ALIGN_EPI = false, bool SP2 = false>
; __device__ __forceinline__ void gemm_phase(LAS unsigned char* lds, const Gemm g, const Sched& S, const Epi& E, int wid) {
;     ...
;             PG8_WAIT_V(8); PG8_WAIT_L(0); PG8_BAR; PG8_MMA(0, 0, At, B0); PG8_MMA(0, 1, At, B1); PG8_BAR; PG8_SCHED;
;             PG8_LDA(At, 0, 1); PG8_STAGE(PG8_SB(0, 0), b2, voffB); PG8_STAGE(PG8_SB(0, 1), b2 + hstepB, voffB); PG8_STAGE(PG8_SA(0, 0), a2, voffA);
;             PG8_WAIT_V(8); PG8_WAIT_L(0); PG8_BAR; PG8_MMA(1, 0, At, B0); PG8_MMA(1, 1, At, B1); PG8_BAR; PG8_SCHED;
;             PG8_LDB(B0, 1, 0); PG8_LDB(B1, 1, 1); PG8_SCHED; PG8_LDA(At, 1, 0); PG8_STAGE(PG8_SA(0, 1), a2 + hstepA, voffA);
;             PG8_WAIT_V(8); PG8_WAIT_L(0); PG8_BAR; PG8_MMA(0, 0, At, B0); PG8_MMA(0, 1, At, B1); PG8_BAR; PG8_SCHED;
;             PG8_LDA(At, 1, 1); PG8_STAGE(PG8_SB(1, 0), b3, voffB); PG8_STAGE(PG8_SB(1, 1), b3 + hstepB, voffB); PG8_STAGE(PG8_SA(1, 0), a3, voffA);
	s_setprio 1
	s_waitcnt lgkmcnt(0)
	v_mfma_f32_16x16x32_bf16 v[92:95], v[104:107], v[148:151], v[92:95]
	v_mfma_f32_16x16x32_bf16 v[28:31], v[112:115], v[148:151], v[28:31]
	v_mfma_f32_16x16x32_bf16 v[88:91], v[104:107], v[168:171], v[88:91]
	v_mfma_f32_16x16x32_bf16 v[4:7], v[112:115], v[168:171], v[4:7]
	v_mfma_f32_16x16x32_bf16 v[80:83], v[104:107], v[200:203], v[80:83]
	v_mfma_f32_16x16x32_bf16 v[24:27], v[112:115], v[200:203], v[24:27]
	v_mfma_f32_16x16x32_bf16 v[72:75], v[104:107], v[208:211], v[72:75]
	v_mfma_f32_16x16x32_bf16 v[16:19], v[112:115], v[208:211], v[16:19]
	v_mfma_f32_16x16x32_bf16 v[92:95], v[108:111], v[164:167], v[92:95]
	v_mfma_f32_16x16x32_bf16 v[28:31], v[116:119], v[164:167], v[28:31]
	v_mfma_f32_16x16x32_bf16 v[88:91], v[108:111], v[186:189], v[88:91]
	v_mfma_f32_16x16x32_bf16 v[4:7], v[116:119], v[186:189], v[4:7]
	v_mfma_f32_16x16x32_bf16 v[80:83], v[108:111], v[204:207], v[80:83]
	v_mfma_f32_16x16x32_bf16 v[24:27], v[116:119], v[204:207], v[24:27]
	v_mfma_f32_16x16x32_bf16 v[72:75], v[108:111], v[212:215], v[72:75]
	v_mfma_f32_16x16x32_bf16 v[16:19], v[116:119], v[212:215], v[16:19]
	s_setprio 0
	s_setprio 1
	v_mfma_f32_16x16x32_bf16 v[84:87], v[120:123], v[148:151], v[84:87]
	v_mfma_f32_16x16x32_bf16 v[20:23], v[128:131], v[148:151], v[20:23]
	v_mfma_f32_16x16x32_bf16 v[76:79], v[120:123], v[168:171], v[76:79]
	v_mfma_f32_16x16x32_bf16 v[0:3], v[128:131], v[168:171], v[0:3]
	v_mfma_f32_16x16x32_bf16 v[68:71], v[120:123], v[200:203], v[68:71]
	v_mfma_f32_16x16x32_bf16 v[12:15], v[128:131], v[200:203], v[12:15]
	v_mfma_f32_16x16x32_bf16 v[64:67], v[120:123], v[208:211], v[64:67]
	v_mfma_f32_16x16x32_bf16 v[8:11], v[128:131], v[208:211], v[8:11]
	v_mfma_f32_16x16x32_bf16 v[84:87], v[124:127], v[164:167], v[84:87]
	v_mfma_f32_16x16x32_bf16 v[20:23], v[132:135], v[164:167], v[20:23]
	v_mfma_f32_16x16x32_bf16 v[76:79], v[124:127], v[186:189], v[76:79]
	v_mfma_f32_16x16x32_bf16 v[0:3], v[132:135], v[186:189], v[0:3]
	v_mfma_f32_16x16x32_bf16 v[68:71], v[124:127], v[204:207], v[68:71]
	v_mfma_f32_16x16x32_bf16 v[12:15], v[132:135], v[204:207], v[12:15]
	v_mfma_f32_16x16x32_bf16 v[64:67], v[124:127], v[212:215], v[64:67]
	v_mfma_f32_16x16x32_bf16 v[8:11], v[132:135], v[212:215], v[8:11]
	s_setprio 0
	s_barrier
	s_add_i32 s54, 0, 0x18000
	s_add_i32 s55, 0, 0x1c000
	v_add_u32_e32 v116, s54, v228
	v_add_u32_e32 v132, s55, v228
	s_add_u32 s48, s48, 0x80000
	s_addc_u32 s49, s49, 0
	s_mov_b32 m0, s79
	s_add_u32 s100, s48, 0xfff80000
	s_addc_u32 s101, s49, -1
	global_load_lds_dwordx4 v176, s[100:101]
	s_mov_b32 m0, s81
	ds_read_b128 v[104:107], v116
	ds_read_b128 v[108:111], v116 offset:1024
	ds_read_b128 v[112:115], v116 offset:2048
	ds_read_b128 v[116:119], v116 offset:3072
	global_load_lds_dwordx4 v174, s[100:101]
	s_mov_b32 m0, s77
	ds_read_b128 v[120:123], v132
	ds_read_b128 v[124:127], v132 offset:1024
	ds_read_b128 v[128:131], v132 offset:2048
	ds_read_b128 v[132:135], v132 offset:3072
	global_load_lds_dwordx4 v176, s[48:49]
	s_mov_b32 m0, s4
	ds_read_b128 v[148:151], v231 offset:32768
	ds_read_b128 v[164:167], v231 offset:33792
	ds_read_b128 v[168:171], v231 offset:34816
	ds_read_b128 v[186:189], v231 offset:35840
	global_load_lds_dwordx4 v174, s[48:49]
	ds_read_b128 v[200:203], v231 offset:36864
	ds_read_b128 v[204:207], v231 offset:37888
	ds_read_b128 v[208:211], v231 offset:38912
	ds_read_b128 v[212:215], v231 offset:39936
	s_waitcnt vmcnt(8)
	s_waitcnt lgkmcnt(0)
	s_barrier
; #define PG8_STAGE(bufoff, gbase, voff) do { _Pragma("unroll") for (int _i = 0; _i < 2; ++_i) \
;         __builtin_amdgcn_global_load_lds((const unsigned*)((const char*)(gbase) + (voff)[_i]), (LAS unsigned*)(lds + (bufoff) + ldsw + _i * 8192), 16, 0, 0); } while (0)
; #define PG8_LDA(dst, b, h) do { _Pragma("unroll") for (int m = 0; m < 4; ++m) _Pragma("unroll") for (int k = 0; k < 2; ++k) dst[m][k] = *(const LAS bf16x8*)(lds + PG8_SA(b, h) + aoff + m * 2048 + k * 1024); } while (0)
; #define PG8_LDB(dst, b, h) do { _Pragma("unroll") for (int n = 0; n < 2; ++n) _Pragma("unroll") for (int k = 0; k < 2; ++k) dst[n][k] = *(const LAS bf16x8*)(lds + PG8_SB(b, h) + boff + n * 2048 + k * 1024); } while (0)
; #define PG8_MMA(ai, bj, At, Bt) do { __builtin_amdgcn_s_setprio(1); _Pragma("unroll") for (int m = 0; m < 4; ++m) _Pragma("unroll") for (int n = 0; n < 2; ++n) _Pragma("unroll") for (int k = 0; k < 2; ++k) \
;         acc[ai][bj][m][n] = __builtin_amdgcn_mfma_f32_16x16x32_bf16(Bt[n][k], At[m][k], acc[ai][bj][m][n], 0, 0, 0); __builtin_amdgcn_s_setprio(0); } while (0)
; #define PG8_WAIT_V(n) asm volatile("s_waitcnt vmcnt(" #n ")" ::: "memory")
; #define PG8_WAIT_L(n) asm volatile("s_waitcnt lgkmcnt(" #n ")" ::: "memory")
; #define PG8_BAR __builtin_amdgcn_s_barrier()
; #define PG8_SCHED __builtin_amdgcn_sched_barrier(0)
; template <class Epi, class Sched, bool ALIGN_EPI = false, bool SP2 = false>
; __device__ __forceinline__ void gemm_phase(LAS unsigned char* lds, const Gemm g, const Sched& S, const Epi& E, int wid) {
;     ...
;         for (int t = 0; t < nt; t += 2) {
;             const bool last = (t == nt - 2);
;             const char* a1 = cA + (size_t)(t + 1) * kstep;
;             const char* a2 = last ? nA : cA + (size_t)(t + 2) * kstep; const char* b2 = last ? nB : cB + (size_t)(t + 2) * kstep;
;     ...
;             PG8_LDB(B0, 1, 0); PG8_LDB(B1, 1, 1); PG8_SCHED; PG8_LDA(At, 1, 0); PG8_STAGE(PG8_SA(0, 1), a2 + hstepA, voffA);
;             PG8_WAIT_V(8); PG8_WAIT_L(0); PG8_BAR; PG8_MMA(0, 0, At, B0); PG8_MMA(0, 1, At, B1); PG8_BAR; PG8_SCHED;
;             PG8_LDA(At, 1, 1); PG8_STAGE(PG8_SB(1, 0), b3, voffB); PG8_STAGE(PG8_SB(1, 1), b3 + hstepB, voffB); PG8_STAGE(PG8_SA(1, 0), a3, voffA);
;             PG8_WAIT_V(8); PG8_WAIT_L(0); PG8_BAR; PG8_MMA(1, 0, At, B0); PG8_MMA(1, 1, At, B1); PG8_BAR; PG8_SCHED;
	s_setprio 1
	s_waitcnt lgkmcnt(0)
	v_mfma_f32_16x16x32_bf16 v[160:163], v[104:107], v[148:151], v[160:163]
	v_mfma_f32_16x16x32_bf16 v[60:63], v[112:115], v[148:151], v[60:63]
	v_mfma_f32_16x16x32_bf16 v[152:155], v[104:107], v[168:171], v[152:155]
	v_mfma_f32_16x16x32_bf16 v[36:39], v[112:115], v[168:171], v[36:39]
	v_mfma_f32_16x16x32_bf16 v[140:143], v[104:107], v[200:203], v[140:143]
	v_mfma_f32_16x16x32_bf16 v[56:59], v[112:115], v[200:203], v[56:59]
	v_mfma_f32_16x16x32_bf16 v[100:103], v[104:107], v[208:211], v[100:103]
	v_mfma_f32_16x16x32_bf16 v[48:51], v[112:115], v[208:211], v[48:51]
	v_mfma_f32_16x16x32_bf16 v[160:163], v[108:111], v[164:167], v[160:163]
	v_mfma_f32_16x16x32_bf16 v[60:63], v[116:119], v[164:167], v[60:63]
	v_mfma_f32_16x16x32_bf16 v[152:155], v[108:111], v[186:189], v[152:155]
	v_mfma_f32_16x16x32_bf16 v[36:39], v[116:119], v[186:189], v[36:39]
	v_mfma_f32_16x16x32_bf16 v[140:143], v[108:111], v[204:207], v[140:143]
	v_mfma_f32_16x16x32_bf16 v[56:59], v[116:119], v[204:207], v[56:59]
	v_mfma_f32_16x16x32_bf16 v[100:103], v[108:111], v[212:215], v[100:103]
	v_mfma_f32_16x16x32_bf16 v[48:51], v[116:119], v[212:215], v[48:51]
	s_setprio 0
	s_setprio 1
	v_mfma_f32_16x16x32_bf16 v[156:159], v[120:123], v[148:151], v[156:159]
	v_mfma_f32_16x16x32_bf16 v[52:55], v[128:131], v[148:151], v[52:55]
	v_mfma_f32_16x16x32_bf16 v[144:147], v[120:123], v[168:171], v[144:147]
	v_mfma_f32_16x16x32_bf16 v[32:35], v[128:131], v[168:171], v[32:35]
	v_mfma_f32_16x16x32_bf16 v[136:139], v[120:123], v[200:203], v[136:139]
	v_mfma_f32_16x16x32_bf16 v[44:47], v[128:131], v[200:203], v[44:47]
	v_mfma_f32_16x16x32_bf16 v[96:99], v[120:123], v[208:211], v[96:99]
	v_mfma_f32_16x16x32_bf16 v[40:43], v[128:131], v[208:211], v[40:43]
	v_mfma_f32_16x16x32_bf16 v[156:159], v[124:127], v[164:167], v[156:159]
	v_mfma_f32_16x16x32_bf16 v[52:55], v[132:135], v[164:167], v[52:55]
	v_mfma_f32_16x16x32_bf16 v[148:151], v[124:127], v[186:189], v[144:147]
	v_mfma_f32_16x16x32_bf16 v[32:35], v[132:135], v[186:189], v[32:35]
	v_mfma_f32_16x16x32_bf16 v[136:139], v[124:127], v[204:207], v[136:139]
	v_mfma_f32_16x16x32_bf16 v[44:47], v[132:135], v[204:207], v[44:47]
	v_mfma_f32_16x16x32_bf16 v[96:99], v[124:127], v[212:215], v[96:99]
	v_mfma_f32_16x16x32_bf16 v[40:43], v[132:135], v[212:215], v[40:43]
	s_setprio 0
	s_barrier
	s_add_i32 s48, s54, s89
	s_mov_b32 m0, s48
	s_add_u32 s100, vcc_lo, 0x80
	s_addc_u32 s101, vcc_hi, 0
	global_load_lds_dwordx4 v192, s[100:101]
	s_add_i32 m0, s48, 0x2000
	ds_read_b128 v[144:147], v231 offset:49152
	ds_read_b128 v[164:167], v231 offset:50176
	s_add_u32 s48, vcc_lo, 0x80080
	s_addc_u32 s49, vcc_hi, 0
	s_add_i32 s54, s55, s89
	global_load_lds_dwordx4 v172, s[100:101]
	s_mov_b32 m0, s54
	ds_read_b128 v[168:171], v231 offset:51200
	ds_read_b128 v[186:189], v231 offset:52224
	global_load_lds_dwordx4 v192, s[48:49]
	s_add_i32 m0, s54, 0x2000
	ds_read_b128 v[200:203], v231 offset:53248
	ds_read_b128 v[204:207], v231 offset:54272
	global_load_lds_dwordx4 v172, s[48:49]
	ds_read_b128 v[208:211], v231 offset:55296
	ds_read_b128 v[212:215], v231 offset:56320
	s_waitcnt vmcnt(6)
	s_waitcnt lgkmcnt(0)
	s_barrier
	s_setprio 1
	s_waitcnt lgkmcnt(0)
	v_mfma_f32_16x16x32_bf16 v[92:95], v[104:107], v[144:147], v[92:95]
	v_mfma_f32_16x16x32_bf16 v[28:31], v[112:115], v[144:147], v[28:31]
	v_mfma_f32_16x16x32_bf16 v[88:91], v[104:107], v[168:171], v[88:91]
	v_mfma_f32_16x16x32_bf16 v[4:7], v[112:115], v[168:171], v[4:7]
	v_mfma_f32_16x16x32_bf16 v[80:83], v[104:107], v[200:203], v[80:83]
	v_mfma_f32_16x16x32_bf16 v[24:27], v[112:115], v[200:203], v[24:27]
	v_mfma_f32_16x16x32_bf16 v[72:75], v[104:107], v[208:211], v[72:75]
	v_mfma_f32_16x16x32_bf16 v[16:19], v[112:115], v[208:211], v[16:19]
	v_mfma_f32_16x16x32_bf16 v[92:95], v[108:111], v[164:167], v[92:95]
	v_mfma_f32_16x16x32_bf16 v[28:31], v[116:119], v[164:167], v[28:31]
	v_mfma_f32_16x16x32_bf16 v[88:91], v[108:111], v[186:189], v[88:91]
	v_mfma_f32_16x16x32_bf16 v[4:7], v[116:119], v[186:189], v[4:7]
	v_mfma_f32_16x16x32_bf16 v[80:83], v[108:111], v[204:207], v[80:83]
	v_mfma_f32_16x16x32_bf16 v[24:27], v[116:119], v[204:207], v[24:27]
	v_mfma_f32_16x16x32_bf16 v[72:75], v[108:111], v[212:215], v[72:75]
	v_mfma_f32_16x16x32_bf16 v[16:19], v[116:119], v[212:215], v[16:19]
	s_setprio 0
	s_setprio 1
	v_mfma_f32_16x16x32_bf16 v[84:87], v[120:123], v[144:147], v[84:87]
	v_mfma_f32_16x16x32_bf16 v[20:23], v[128:131], v[144:147], v[20:23]
	v_mfma_f32_16x16x32_bf16 v[76:79], v[120:123], v[168:171], v[76:79]
	v_mfma_f32_16x16x32_bf16 v[0:3], v[128:131], v[168:171], v[0:3]
	v_mfma_f32_16x16x32_bf16 v[68:71], v[120:123], v[200:203], v[68:71]
	v_mfma_f32_16x16x32_bf16 v[12:15], v[128:131], v[200:203], v[12:15]
	v_mfma_f32_16x16x32_bf16 v[64:67], v[120:123], v[208:211], v[64:67]
	v_mfma_f32_16x16x32_bf16 v[8:11], v[128:131], v[208:211], v[8:11]
	v_mfma_f32_16x16x32_bf16 v[84:87], v[124:127], v[164:167], v[84:87]
	v_mfma_f32_16x16x32_bf16 v[20:23], v[132:135], v[164:167], v[20:23]
	v_mfma_f32_16x16x32_bf16 v[76:79], v[124:127], v[186:189], v[76:79]
	v_mfma_f32_16x16x32_bf16 v[0:3], v[132:135], v[186:189], v[0:3]
	v_mfma_f32_16x16x32_bf16 v[68:71], v[124:127], v[204:207], v[68:71]
	v_mfma_f32_16x16x32_bf16 v[12:15], v[132:135], v[204:207], v[12:15]
	v_mfma_f32_16x16x32_bf16 v[64:67], v[124:127], v[212:215], v[64:67]
	v_mfma_f32_16x16x32_bf16 v[8:11], v[132:135], v[212:215], v[8:11]
	s_setprio 0
	s_barrier
	s_add_i32 s93, s93, 2
	s_add_u32 s60, s60, 0x100
	s_addc_u32 s61, s61, 0
	s_cmp_gt_u32 s93, 29
	s_mov_b64 s[54:55], s[56:57]
	s_cbranch_scc0 .LBB0_968
	s_and_b64 vcc, exec, s[82:83]
	s_cbranch_vccz .LBB0_971
	s_barrier
